# cvhost split slot: gains multiply + LDS transpose at step A (results read back into the data registers), pack + sector stores + next loads at step B; original strict vmcnt(0) waits
# baseline (speedup 1.0000x reference)
; #define GAS __attribute__((address_space(1)))
; __device__ __forceinline__ unsigned cvt_pk_bf16(float lo, float hi) { unsigned r; asm volatile("v_cvt_pk_bf16_f32 %0, %1, %2" : "=v"(r) : "v"(lo), "v"(hi)); return r; }
; template <int NB>
; __device__ __forceinline__ void p0_batch(int it0, int stride, int lane, const P0Ptrs& a) {
;     ...
;     for (int q = 0; q < NB; ++q) {
;         const float gs = d[q].gs; const bool hk = d[q].ks != nullptr;
;         const f32x4 t0 = hk ? s0[q] * gs : (f32x4){gs, gs, gs, gs}, t1 = hk ? s1[q] * gs : (f32x4){gs, gs, gs, gs};
; #pragma unroll
;         for (int i = 0; i < 4; ++i) { v[q][i] *= t0[i]; v[q][4 + i] *= t1[i]; }
;         if (d[q].dst) {
; #pragma unroll
;             for (int e = 0; e < 4; ++e) { u32x4 o; o.x = cvt_pk_bf16(v[q][0][e], v[q][1][e]); o.y = cvt_pk_bf16(v[q][2][e], v[q][3][e]); o.z = cvt_pk_bf16(v[q][4][e], v[q][5][e]); o.w = cvt_pk_bf16(v[q][6][e], v[q][7][e]);
;                 *(GAS u32x4*)(d[q].dst + (size_t)e * d[q].ldt) = o; } }
;     }
.LBB0_759:
	v_lshl_add_u64 v[112:113], s[28:29], 0, v[146:147]
	s_mov_b64 s[54:55], 0x18fc0000
	s_mov_b32 m0, s78
	v_lshl_add_u64 v[100:101], v[112:113], 0, s[54:55]
	s_waitcnt vmcnt(0)
	s_barrier
	global_load_lds_dwordx4 v[100:101], off
	v_lshl_add_u64 v[100:101], v[112:113], 0, s[38:39]
	s_add_i32 m0, s78, 0x2000
	v_lshl_add_u64 v[136:137], s[28:29], 0, v[144:145]
	global_load_lds_dwordx4 v[100:101], off
	v_lshl_add_u64 v[100:101], v[136:137], 0, s[40:41]
	s_add_i32 m0, s78, 0x4000
	v_lshl_add_u64 v[134:135], s[28:29], 0, v[148:149]
	global_load_lds_dwordx4 v[100:101], off
	v_lshl_add_u64 v[100:101], v[134:135], 0, s[42:43]
	s_mov_b32 m0, s58
	global_load_lds_dwordx4 v[100:101], off
	v_lshl_add_u64 v[100:101], v[134:135], 0, s[44:45]
	s_mov_b32 m0, s77
	global_load_lds_dwordx4 v[100:101], off
	s_add_i32 s98, s87, -1
	s_cmp_gt_u32 s98, 19
	s_cbranch_scc1 .Lcv_xdone
	s_cmp_gt_u32 s32, 6
	s_cbranch_scc1 .Lcv_nomul
	v_mul_f32_e32 v238, v237, v238
	v_mul_f32_e32 v239, v237, v239
	v_mul_f32_e32 v240, v237, v240
	v_mul_f32_e32 v241, v237, v241
	v_mul_f32_e32 v242, v237, v242
	v_mul_f32_e32 v243, v237, v243
	v_mul_f32_e32 v244, v237, v244
	v_mul_f32_e32 v245, v237, v245
.Lcv_nomul:
	v_readfirstlane_b32 s98, v0
	v_and_b32_e32 v76, 63, v0
	v_lshrrev_b32_e32 v77, 2, v76
	v_and_b32_e32 v78, 3, v76
	s_lshr_b32 s98, s98, 6
	s_lshl_b32 s99, s98, 10
	s_cmp_lt_u32 s98, 6
	s_mov_b32 s98, 0x24c00
	s_cselect_b32 s98, 0x1e800, s98
	s_add_i32 s98, s98, s99
	v_lshlrev_b32_e32 v81, 8, v78
	v_lshl_add_u32 v81, v77, 2, v81
	v_add_u32_e32 v81, s98, v81
	v_lshl_add_u32 v82, v76, 4, s98
	ds_write_b32 v81, v238
	ds_write_b32 v81, v239 offset:64
	ds_write_b32 v81, v240 offset:128
	ds_write_b32 v81, v241 offset:192
	ds_read_b128 v[238:241], v82
	ds_write_b32 v81, v242
	ds_write_b32 v81, v243 offset:64
	ds_write_b32 v81, v244 offset:128
	ds_write_b32 v81, v245 offset:192
	ds_read_b128 v[242:245], v82

; #define GAS __attribute__((address_space(1)))
; __device__ __forceinline__ unsigned cvt_pk_bf16(float lo, float hi) { unsigned r; asm volatile("v_cvt_pk_bf16_f32 %0, %1, %2" : "=v"(r) : "v"(lo), "v"(hi)); return r; }
; template <int NB>
; __device__ __forceinline__ void p0_batch(int it0, int stride, int lane, const P0Ptrs& a) {
;     ...
;         if (d[q].dst) {
; #pragma unroll
;             for (int e = 0; e < 4; ++e) { u32x4 o; o.x = cvt_pk_bf16(v[q][0][e], v[q][1][e]); o.y = cvt_pk_bf16(v[q][2][e], v[q][3][e]); o.z = cvt_pk_bf16(v[q][4][e], v[q][5][e]); o.w = cvt_pk_bf16(v[q][6][e], v[q][7][e]);
;                 *(GAS u32x4*)(d[q].dst + (size_t)e * d[q].ldt) = o; } }
;     }
.LBB0_766:
	s_cmp_gt_u32 s87, 20
	s_cbranch_scc1 .Lcv_done
	s_cmp_eq_u32 s87, 0
	s_cbranch_scc1 .Lcv_nocons
	v_and_b32_e32 v84, 63, v0
	v_lshrrev_b32_e32 v85, 2, v84
	v_and_b32_e32 v86, 3, v84
	v_lshlrev_b32_e32 v89, 3, v86
	v_mad_u32_u24 v89, v85, s91, v89
	s_lshl_b32 s98, s91, 4
	s_add_u32 s98, s92, s98
	s_addc_u32 s99, s93, 0
	s_waitcnt lgkmcnt(0)
	v_cvt_pk_bf16_f32 v238, v238, v239
	v_cvt_pk_bf16_f32 v239, v240, v241
	v_cvt_pk_bf16_f32 v242, v242, v243
	v_cvt_pk_bf16_f32 v243, v244, v245
	global_store_dwordx2 v89, v[238:239], s[92:93]
	global_store_dwordx2 v89, v[242:243], s[98:99]
	s_add_u32 s92, s92, 32
	s_addc_u32 s93, s93, 0

; template <int NB>
; __device__ __forceinline__ void p0_batch(int it0, int stride, int lane, const P0Ptrs& a) {
;     f32x4 v[NB][8], s0[NB], s1[NB]; P0Desc d[NB];
; #pragma unroll
;     for (int q = 0; q < NB; ++q) { const bool ok = it0 < NFAST / 4; d[q] = p0_desc(p0_super(ok ? it0 : 0, q), lane, a); if (!ok) d[q].dst = nullptr;
; #pragma unroll
;         for (int i = 0; i < 8; ++i) v[q][i] = __builtin_nontemporal_load((const f32x4*)(d[q].src + (size_t)i * d[q].nsrc));
;         const float* kp = d[q].ks ? d[q].ks : a.ffn_g;
;         s0[q] = *(const f32x4*)(kp); s1[q] = *(const f32x4*)(kp + 4); }
.Lcv_s2done:
.Lcv_loads:
	v_and_b32_e32 v84, 63, v0
	v_lshrrev_b32_e32 v85, 2, v84
	v_and_b32_e32 v86, 3, v84
	v_lshlrev_b32_e32 v86, 4, v86
	v_mad_u32_u24 v87, v85, s90, v86
	v_lshlrev_b32_e32 v88, 2, v85
	s_lshl_b32 s98, s90, 4
	global_load_dwordx4 v[238:241], v87, s[88:89] nt
	global_load_dwordx4 v[242:245], v87, s[88:89] offset:64 nt
	global_load_dword v237, v88, s[94:95]
	s_add_u32 s88, s88, s98
	s_addc_u32 s89, s89, 0
	s_add_u32 s94, s94, 64
	s_addc_u32 s95, s95, 0
	s_and_b32 s98, s87, 3
	s_cmp_lg_u32 s98, 3
	s_cbranch_scc1 .Lcv_inc
	s_cmp_gt_u32 s87, 18
	s_cbranch_scc1 .Lcv_inc
	s_add_i32 s99, s32, 1
	s_movk_i32 s98, 0x78
	s_cmp_lt_u32 s99, 7
	s_cselect_b32 s98, 0x60, s98
	s_cmp_eq_u32 s99, 0
	s_cselect_b32 s98, 0x50, s98
	s_cselect_b32 s99, 0, 0x58
	s_load_dwordx2 s[88:89], s[100:101], s98
	s_cmp_eq_u32 s99, 0
	s_cbranch_scc0 .Lcv_s1b_s
	s_bfe_u32 s99, s2, 0x50003
	s_cmp_lt_u32 s99, 16
	s_cselect_b32 s99, 64, 0x48

; #define SBAR() __builtin_amdgcn_sched_barrier(0)
; #define DMA_K(t, bf) do { if (ABL & 8) break; const char* kb_ = Kt + (size_t)(t) * KSTEP; LAS unsigned char* kd_ = Kl + (bf) * SHM_K + wid * 1024; \
;     glds16(kb_ + voffK, kd_); glds16(kb_ + 128 + voffK, kd_ + 8192); glds16(Pt + (size_t)(t) * PSTEP + voffP, kd_ + 16384); } while (0)
; #define DMA_V(t, bf) do { if (ABL & 8) break; const char* vb_ = Kt + 256 + (size_t)(t) * KSTEP; LAS unsigned char* vd_ = Vl + (bf) * SHM_V + wid * 1024; \
;     glds16(vb_ + voffV, vd_); glds16(vb_ + (size_t)32 * LDKV * 2 + voffV, vd_ + 8192); } while (0)
; #define END_STEP() do { if (!(ABL & 8)) { asm volatile("s_waitcnt vmcnt(0)" ::: "memory"); __syncthreads(); } } while (0)
; #define RESC(a) do { if (__any((a) < 1.f)) { if (hi == 0) al_l[r32] = (a); asm volatile("s_waitcnt lgkmcnt(0)" ::: "memory"); \
;     _Pragma("unroll") for (int d = 0; d < 4; ++d) _Pragma("unroll") for (int r = 0; r < 16; ++r) o[d][r] *= al_l[crow(r, hi)]; } } while (0)
; #define PV_TILE(VB, C0, C1, alC, PAR) do { s16x4 va_[8], vb_[8]; float ma_ = 0.f, mb_ = 0.f, mn_ = 0.f; VRD8(VB, 0, va_); SBAR(); \
;     PV_BLK(VB, 0, va_, vb_, C0, C1, PAR); if (PAR) { DECIDE(alC); } SBAR(); \
;     PV_BLK(VB, 1, vb_, va_, C0, C1, PAR); PV_BLK(VB, 2, va_, vb_, C0, C1, PAR); PV_BLK(VB, 3, vb_, va_, C0, C1, PAR); } while (0)
; template <int ABL> __device__ __forceinline__ void attn_unit(int b, int h, int qb, const bf16_t* Q, const bf16_t* KV, const bf16_t* KPE, bf16_t* MG, float* ssqa, LAS unsigned char* L) {
;     ...
;   for (int j = 1; j + 1 < NT; j += 2) {
;     SBAR(); QK_TILE(Kl + SHM_K, pB0, pB1, pA0, pA1, alA, true);
;     SBAR(); PAR_ONLY(pB0, pB1, alB); SBAR(); PV_TILE(Vp, pB0, pB1, alB, false);
;     RESC(alB);
;     END_STEP(); DMA_K(j + 2, 1); DMA_V(j + 1, 0);
;     SBAR(); QK_TILE(Kl, pA0, pA1, pB0, pB1, alB, true);
;     SBAR(); PAR_ONLY(pA0, pA1, alA); SBAR(); PV_TILE(Vp + SHM_V, pA0, pA1, alA, false);
;     RESC(alA);
;     END_STEP(); if (j + 3 < NT) DMA_K(j + 3, 0); DMA_V(j + 2, 1);
;   }
.Lcv_inc:
	s_add_i32 s87, s87, 1
.Lcv_done:
	v_exp_f32_e32 v1, v69
	v_exp_f32_e32 v112, v70
	v_exp_f32_e32 v113, v71
	v_exp_f32_e32 v110, v72
	v_exp_f32_e32 v111, v73
	v_exp_f32_e32 v108, v74
	v_exp_f32_e32 v109, v75
	v_exp_f32_e32 v106, v76
	v_exp_f32_e32 v107, v77
	v_exp_f32_e32 v104, v78
	v_exp_f32_e32 v105, v79
	v_exp_f32_e32 v102, v80
	v_exp_f32_e32 v103, v81
	v_exp_f32_e32 v100, v82
	v_exp_f32_e32 v101, v83
	v_add_f32_e32 v69, v201, v202
	v_fmac_f32_e32 v69, v2, v180
	v_add_f32_e32 v2, v205, v206
	v_fmac_f32_e32 v2, v69, v203
	s_andn2_b64 vcc, exec, s[54:55]
	s_cbranch_vccz .LBB0_770
	v_mov_b32_e32 v180, v204
	s_branch .LBB0_754
